# prep0 per-token loop: 22 ds_bpermute shuffles per token (norm reductions and rope partner exchange) replaced by DPP moves
# baseline (speedup 1.0000x reference)
.LBB0_990:
	s_or_b64 exec, exec, s[18:19]
	v_and_b32_e32 v45, 0xffff0000, v28
	v_lshlrev_b32_e32 v44, 16, v28
	v_and_b32_e32 v47, 0xffff0000, v29
	v_lshlrev_b32_e32 v46, 16, v29
	v_pk_mul_f32 v[28:29], v[44:45], v[44:45]
	v_pk_mul_f32 v[34:35], v[46:47], v[46:47]
	v_add_f32_e32 v28, v28, v29
	s_waitcnt lgkmcnt(2)
	v_and_b32_e32 v71, 0xffff0000, v30
	v_lshlrev_b32_e32 v70, 16, v30
	v_add_f32_e32 v28, v34, v28
	s_waitcnt lgkmcnt(0)
	v_and_b32_e32 v73, 0xffff0000, v31
	v_lshlrev_b32_e32 v72, 16, v31
	v_pk_mul_f32 v[30:31], v[70:71], v[70:71]
	v_add_f32_e32 v28, v35, v28
	v_add_f32_e32 v28, v30, v28
	v_pk_mul_f32 v[32:33], v[72:73], v[72:73]
	v_add_f32_e32 v28, v31, v28
	v_add_f32_e32 v28, v32, v28
	v_add_f32_e32 v28, v33, v28
	s_nop 1
	v_mov_b32_dpp v29, v28 quad_perm:[1,0,3,2] row_mask:0xf bank_mask:0xf
	s_movk_i32 s0, 0x2000
	v_cmp_gt_i32_e32 vcc, s0, v64
	s_movk_i32 s0, 0x1fff
	v_cmp_lt_i32_e64 s[42:43], s0, v64
	s_waitcnt lgkmcnt(0)
	v_add_f32_e32 v28, v28, v29
	s_nop 1
	v_mov_b32_dpp v29, v28 quad_perm:[2,3,0,1] row_mask:0xf bank_mask:0xf
	s_mov_b32 s0, 0x800000
	v_bfe_u32 v30, v64, 6, 6
	v_and_b32_e32 v31, 63, v64
	v_cndmask_b32_e64 v30, v31, v30, s[4:5]
	s_waitcnt lgkmcnt(0)
	v_add_f32_e32 v28, v28, v29
	s_nop 1
	v_mov_b32_dpp v29, v28 row_half_mirror row_mask:0xf bank_mask:0xf
	v_lshl_add_u32 v40, v30, 6, v74
	s_waitcnt lgkmcnt(0)
	v_add_f32_e32 v28, v28, v29
	v_fmamk_f32 v28, v28, 0x3c800000, v132
	v_mul_f32_e32 v29, 0x4b800000, v28
	v_cmp_gt_f32_e64 s[44:45], s0, v28
	s_nop 1
	v_cndmask_b32_e64 v28, v28, v29, s[44:45]
	v_rsq_f32_e32 v78, v28
	ds_read_b128 v[28:31], v40
	ds_read_b128 v[36:39], v40 offset:16
	ds_read_b128 v[32:35], v40 offset:4096
	ds_read_b128 v[40:43], v40 offset:4112
	v_mul_f32_e32 v79, 0x45800000, v78
	v_cndmask_b32_e64 v78, v78, v79, s[44:45]
	v_pk_mul_f32 v[44:45], v[78:79], v[44:45] op_sel_hi:[0,1]
	v_pk_mul_f32 v[46:47], v[78:79], v[46:47] op_sel_hi:[0,1]
	v_pk_mul_f32 v[70:71], v[78:79], v[70:71] op_sel_hi:[0,1]
	v_pk_mul_f32 v[72:73], v[78:79], v[72:73] op_sel_hi:[0,1]
	v_pk_mul_f32 v[44:45], v[48:49], v[44:45]
	v_pk_mul_f32 v[46:47], v[50:51], v[46:47]
	v_pk_mul_f32 v[70:71], v[52:53], v[70:71]
	v_pk_mul_f32 v[72:73], v[54:55], v[72:73]
	s_and_saveexec_b64 s[36:37], s[42:43]
	s_cbranch_execz .LBB0_992
	s_nop 1
	v_mov_b32_dpp v78, v44 quad_perm:[2,3,0,1] row_mask:0xf bank_mask:0xf
	v_mov_b32_dpp v79, v45 quad_perm:[2,3,0,1] row_mask:0xf bank_mask:0xf
	s_waitcnt lgkmcnt(0)
	v_pk_mul_f32 v[78:79], v[32:33], v[78:79]
	s_nop 0
	v_cndmask_b32_e64 v79, v79, -v79, s[6:7]
	v_cndmask_b32_e64 v78, v78, -v78, s[6:7]
	v_pk_fma_f32 v[44:45], v[28:29], v[44:45], v[78:79]
	s_nop 1
	v_mov_b32_dpp v78, v46 quad_perm:[2,3,0,1] row_mask:0xf bank_mask:0xf
	v_mov_b32_dpp v79, v47 quad_perm:[2,3,0,1] row_mask:0xf bank_mask:0xf
	s_waitcnt lgkmcnt(0)
	v_pk_mul_f32 v[78:79], v[34:35], v[78:79]
	s_nop 0
	v_cndmask_b32_e64 v79, v79, -v79, s[6:7]
	v_cndmask_b32_e64 v78, v78, -v78, s[6:7]
	v_pk_fma_f32 v[46:47], v[30:31], v[46:47], v[78:79]
	s_nop 1
	v_mov_b32_dpp v78, v70 quad_perm:[2,3,0,1] row_mask:0xf bank_mask:0xf
	v_mov_b32_dpp v79, v71 quad_perm:[2,3,0,1] row_mask:0xf bank_mask:0xf
	s_waitcnt lgkmcnt(0)
	v_pk_mul_f32 v[78:79], v[40:41], v[78:79]
	s_nop 0
	v_cndmask_b32_e64 v79, v79, -v79, s[6:7]
	v_cndmask_b32_e64 v78, v78, -v78, s[6:7]
	v_pk_fma_f32 v[70:71], v[36:37], v[70:71], v[78:79]
	s_nop 1
	v_mov_b32_dpp v78, v72 quad_perm:[2,3,0,1] row_mask:0xf bank_mask:0xf
	v_mov_b32_dpp v79, v73 quad_perm:[2,3,0,1] row_mask:0xf bank_mask:0xf
	s_waitcnt lgkmcnt(0)
	v_pk_mul_f32 v[78:79], v[42:43], v[78:79]
	s_nop 0
	v_cndmask_b32_e64 v79, v79, -v79, s[6:7]
	v_cndmask_b32_e64 v78, v78, -v78, s[6:7]
	v_pk_fma_f32 v[72:73], v[38:39], v[72:73], v[78:79]
.LBB0_992:
	s_or_b64 exec, exec, s[36:37]
	v_readlane_b32 s0, v253, 14
	v_lshlrev_b32_e32 v80, 16, v24
	v_and_b32_e32 v81, 0xffff0000, v24
	v_cvt_pk_bf16_f32 v44, v44, v45
	v_cvt_pk_bf16_f32 v45, v46, v47
	v_cvt_pk_bf16_f32 v47, v72, v73
	v_readlane_b32 s1, v253, 15
	v_lshlrev_b32_e32 v72, 16, v25
	v_and_b32_e32 v73, 0xffff0000, v25
	v_pk_mul_f32 v[24:25], v[80:81], v[80:81]
	v_cvt_pk_bf16_f32 v46, v70, v71
	v_lshl_add_u64 v[70:71], s[0:1], 0, v[68:69]
	v_pk_mul_f32 v[78:79], v[72:73], v[72:73]
	v_add_f32_e32 v24, v24, v25
	global_store_dwordx4 v[70:71], v[44:47], off
	v_lshlrev_b32_e32 v70, 16, v26
	v_and_b32_e32 v71, 0xffff0000, v26
	v_add_f32_e32 v24, v78, v24
	v_lshlrev_b32_e32 v46, 16, v27
	v_and_b32_e32 v47, 0xffff0000, v27
	v_pk_mul_f32 v[26:27], v[70:71], v[70:71]
	v_add_f32_e32 v24, v79, v24
	v_add_f32_e32 v24, v26, v24
	v_pk_mul_f32 v[44:45], v[46:47], v[46:47]
	v_add_f32_e32 v24, v27, v24
	v_add_f32_e32 v24, v44, v24
	v_add_f32_e32 v24, v45, v24
	s_nop 1
	v_mov_b32_dpp v25, v24 quad_perm:[1,0,3,2] row_mask:0xf bank_mask:0xf
	s_mov_b32 s0, 0x800000
	s_waitcnt lgkmcnt(0)
	v_add_f32_e32 v24, v24, v25
	s_nop 1
	v_mov_b32_dpp v25, v24 quad_perm:[2,3,0,1] row_mask:0xf bank_mask:0xf
	s_waitcnt lgkmcnt(0)
	v_add_f32_e32 v24, v24, v25
	s_nop 1
	v_mov_b32_dpp v25, v24 row_half_mirror row_mask:0xf bank_mask:0xf
	s_waitcnt lgkmcnt(0)
	v_add_f32_e32 v24, v24, v25
	v_fmamk_f32 v24, v24, 0x3c800000, v132
	v_cmp_gt_f32_e64 s[42:43], s0, v24
	v_mul_f32_e32 v25, 0x4b800000, v24
	s_nop 0
	v_cndmask_b32_e64 v24, v24, v25, s[42:43]
	v_rsq_f32_e32 v24, v24
	s_nop 0
	v_mul_f32_e32 v25, 0x45800000, v24
	v_cndmask_b32_e64 v78, v24, v25, s[42:43]
	v_pk_mul_f32 v[24:25], v[78:79], v[80:81] op_sel_hi:[0,1]
	v_pk_mul_f32 v[26:27], v[78:79], v[72:73] op_sel_hi:[0,1]
	v_pk_mul_f32 v[44:45], v[78:79], v[70:71] op_sel_hi:[0,1]
	v_pk_mul_f32 v[46:47], v[78:79], v[46:47] op_sel_hi:[0,1]
	v_pk_mul_f32 v[24:25], v[4:5], v[24:25]
	v_pk_mul_f32 v[26:27], v[6:7], v[26:27]
	v_pk_mul_f32 v[44:45], v[0:1], v[44:45]
	v_pk_mul_f32 v[46:47], v[2:3], v[46:47]
	s_and_saveexec_b64 s[0:1], vcc
	s_xor_b64 s[18:19], exec, s[0:1]
	s_cbranch_execz .LBB0_996
	s_and_saveexec_b64 s[36:37], s[8:9]
	s_cbranch_execz .LBB0_995
	v_readlane_b32 s0, v253, 14
	v_readlane_b32 s1, v253, 15
	global_store_dwordx4 v[62:63], v[24:27], off
	global_store_dwordx4 v[62:63], v[44:47], off offset:16
	v_lshl_add_u64 v[28:29], s[0:1], 0, v[66:67]
	v_cvt_pk_bf16_f32 v24, v24, v25
	v_cvt_pk_bf16_f32 v25, v26, v27
	v_cvt_pk_bf16_f32 v26, v44, v45
	v_cvt_pk_bf16_f32 v27, v46, v47
	s_mov_b32 s0, 0x400000
	global_store_dwordx4 v[28:29], v[24:27], off
	v_add_co_u32_e32 v28, vcc, s0, v62
	s_nop 0
	v_lshlrev_b32_e32 v24, 16, v8
	v_and_b32_e32 v25, 0xffff0000, v8
	v_lshlrev_b32_e32 v26, 16, v9
	v_and_b32_e32 v27, 0xffff0000, v9
	v_addc_co_u32_e32 v29, vcc, 0, v63, vcc
	v_lshlrev_b32_e32 v8, 16, v10
	v_and_b32_e32 v9, 0xffff0000, v10
	v_lshlrev_b32_e32 v10, 16, v11
	v_and_b32_e32 v11, 0xffff0000, v11
	global_store_dwordx4 v[28:29], v[24:27], off
	global_store_dwordx4 v[28:29], v[8:11], off offset:16

.LBB0_996:
	s_andn2_saveexec_b64 s[18:19], s[18:19]
	s_cbranch_execz .LBB0_987
	s_nop 1
	v_mov_b32_dpp v8, v24 quad_perm:[2,3,0,1] row_mask:0xf bank_mask:0xf
	v_mov_b32_dpp v9, v25 quad_perm:[2,3,0,1] row_mask:0xf bank_mask:0xf
	v_mov_b32_dpp v10, v26 quad_perm:[2,3,0,1] row_mask:0xf bank_mask:0xf
	v_mov_b32_dpp v11, v27 quad_perm:[2,3,0,1] row_mask:0xf bank_mask:0xf
	v_mov_b32_dpp v70, v44 quad_perm:[2,3,0,1] row_mask:0xf bank_mask:0xf
	v_mov_b32_dpp v71, v45 quad_perm:[2,3,0,1] row_mask:0xf bank_mask:0xf
	v_mov_b32_dpp v72, v46 quad_perm:[2,3,0,1] row_mask:0xf bank_mask:0xf
	v_mov_b32_dpp v73, v47 quad_perm:[2,3,0,1] row_mask:0xf bank_mask:0xf
	s_and_saveexec_b64 s[36:37], s[8:9]
	s_cbranch_execz .LBB0_986
	v_and_b32_e32 v78, 0xfff, v64
	v_add_u32_e32 v64, 0xffffe000, v64
	s_waitcnt lgkmcnt(6)
	v_pk_mul_f32 v[8:9], v[32:33], v[8:9]
	v_ashrrev_i32_e32 v64, 12, v64
	v_cndmask_b32_e64 v9, v9, -v9, s[6:7]
	v_cndmask_b32_e64 v8, v8, -v8, s[6:7]
	s_movk_i32 s0, 0x1100
	s_waitcnt lgkmcnt(0)
	v_pk_mul_f32 v[42:43], v[42:43], v[72:73]
	v_pk_mul_f32 v[40:41], v[40:41], v[70:71]
	v_pk_mul_f32 v[10:11], v[34:35], v[10:11]
	v_pk_fma_f32 v[8:9], v[28:29], v[24:25], v[8:9]
	v_mad_i32_i24 v24, v64, s0, v78
	v_cndmask_b32_e64 v43, v43, -v43, s[6:7]
	v_cndmask_b32_e64 v42, v42, -v42, s[6:7]
	v_cndmask_b32_e64 v41, v41, -v41, s[6:7]
	v_cndmask_b32_e64 v40, v40, -v40, s[6:7]
	v_cndmask_b32_e64 v11, v11, -v11, s[6:7]
	v_cndmask_b32_e64 v10, v10, -v10, s[6:7]
	v_ashrrev_i32_e32 v25, 31, v24
	v_pk_fma_f32 v[38:39], v[38:39], v[46:47], v[42:43]
	v_pk_fma_f32 v[36:37], v[36:37], v[44:45], v[40:41]
	v_pk_fma_f32 v[10:11], v[30:31], v[26:27], v[10:11]
	v_lshlrev_b64 v[24:25], 8, v[24:25]
	v_cvt_pk_bf16_f32 v8, v8, v9
	v_cvt_pk_bf16_f32 v9, v10, v11
	v_cvt_pk_bf16_f32 v10, v36, v37
	v_cvt_pk_bf16_f32 v11, v38, v39
	v_lshl_add_u64 v[24:25], v[56:57], 0, v[24:25]
	global_store_dwordx4 v[24:25], v[8:11], off
	s_branch .LBB0_986
